# attention tile 0: 53-op canonicalising row-max tree -> 16-op v_max3 chain (same as the main loop), on top of V^T b32 staging
# baseline (speedup 1.0000x reference)
; __device__ __forceinline__ float bf_lo(unsigned w) { return __uint_as_float(w << 16); }
; __device__ __forceinline__ float bf_hi(unsigned w) { return __uint_as_float(w & 0xffff0000u); }
; #define LOAD_TILE(ti, kreg, vreg) do { const int k0_ = TILE_K0(ti); const size_t grow_ = ((ti) < 4) ? (size_t)(M_ + b * LCTX + k0_) : (size_t)(b * SEQ + k0_); \
;         kreg = *(const u32x4*)(QKV + (grow_ + krow) * NQKV + 1024 + kvh * 64 + 8 * kch); vreg = *(const u32x4*)(QKV + (grow_ + lane) * NQKV + 1280 + kvh * 64 + 8 * w); } while (0)
; #define LOAD_TILE(ti, kreg, vreg) do { const int k0_ = TILE_K0(ti); const size_t grow_ = ((ti) < 4) ? (size_t)(M_ + b * LCTX + k0_) : (size_t)(b * SEQ + k0_); \
;         kreg = *(const u32x4*)(QKV + (grow_ + krow) * NQKV + 1024 + kvh * 64 + 8 * kch); vreg = *(const u32x4*)(QKV + (grow_ + lane) * NQKV + 1280 + kvh * 64 + 8 * w); } while (0)
;     ...
;             const bf16_t* qp = QKV + (size_t)(b * SEQ + qrow) * NQKV + head * 64;
;             float qf[4][8]; float ss = 0.f;
; #pragma unroll
;             for (int d0 = 0; d0 < 4; ++d0) { const u32x4 v = *(const u32x4*)(qp + 8 * (2 * d0 + hi));
;                 qf[d0][0] = bf_lo(v.x); qf[d0][1] = bf_hi(v.x); qf[d0][2] = bf_lo(v.y); qf[d0][3] = bf_hi(v.y); qf[d0][4] = bf_lo(v.z); qf[d0][5] = bf_hi(v.z); qf[d0][6] = bf_lo(v.w); qf[d0][7] = bf_hi(v.w);
; #pragma unroll
;                 for (int i = 0; i < 8; ++i) ss += qf[d0][i] * qf[d0][i]; }
;             ss += __shfl_xor(ss, 32);
;     ...
;         LOAD_TILE(0, kreg, vreg); STORE_TILE(0, 0); LOAD_TILE(1, kreg, vreg); LOAD_TILE(2, kreg2, vreg2); LOAD_TILE(3, kreg3, vreg3); __syncthreads();
.LBB0_503:
	s_lshl_b32 s8, s55, 6
	s_ashr_i32 s22, s55, 9
	s_bfe_u32 s25, s55, 0x20007
	s_and_b32 s13, s8, 0x1fc0
	s_lshl_b32 s8, s25, 2
	v_add_u32_e32 v146, s13, v175
	s_lshl_b32 s24, s22, 13
	s_or_b32 s38, s8, s11
	v_add_u32_e32 v170, s24, v146
	v_mad_i64_i32 v[0:1], s[40:41], v170, s46, v[160:161]
	s_lshl_b32 s8, s38, 7
	v_lshl_add_u64 v[0:1], v[0:1], 0, s[8:9]
	v_lshl_add_u64 v[0:1], v[0:1], 0, v[162:163]
	global_load_dwordx4 v[40:43], v[0:1], off offset:32
	global_load_dwordx4 v[44:47], v[0:1], off offset:96
	global_load_dwordx4 v[32:35], v[0:1], off
	global_load_dwordx4 v[28:31], v[0:1], off offset:64
	global_load_dwordx4 v[8:11], v[148:149], off offset:80
	global_load_dwordx4 v[12:15], v[148:149], off offset:64
	s_nop 0
	global_load_dwordx4 v[0:3], v[148:149], off offset:208
	global_load_dwordx4 v[4:7], v[148:149], off offset:192
	global_load_dwordx4 v[24:27], v[148:149], off offset:16
	global_load_dwordx4 v[36:39], v[148:149], off
	global_load_dwordx4 v[16:19], v[148:149], off offset:144
	s_waitcnt lgkmcnt(0)
	global_load_dwordx4 v[20:23], v[148:149], off offset:128
	v_lshlrev_b64 v[48:49], 8, v[146:147]
	s_lshl_b32 s8, s38, 2
	v_readlane_b32 s72, v255, 4
	v_lshl_add_u64 v[72:73], v[156:157], 0, v[48:49]
	v_mov_b32_e32 v76, s8
	v_readlane_b32 s80, v255, 12
	v_readlane_b32 s81, v255, 13
	global_load_dwordx4 v[48:51], v[72:73], off offset:64
	global_load_dwordx4 v[52:55], v[72:73], off offset:192
	global_load_dwordx4 v[56:59], v[72:73], off offset:16
	global_load_dwordx4 v[60:63], v[72:73], off
	global_load_dwordx4 v[64:67], v[72:73], off offset:144
	global_load_dwordx4 v[68:71], v[72:73], off offset:128
	global_load_dword v124, v76, s[80:81]
	s_lshl_b32 s39, s22, 8
	s_add_i32 s22, s39, 0x10000
	s_ashr_i32 s23, s22, 31
	v_lshl_add_u64 v[74:75], s[22:23], 0, v[154:155]
	s_lshl_b32 s8, s25, 7
	v_readlane_b32 s73, v255, 5
	v_readlane_b32 s74, v255, 6
	v_readlane_b32 s75, v255, 7
	v_readlane_b32 s76, v255, 8
	v_readlane_b32 s77, v255, 9
	v_readlane_b32 s78, v255, 10
	v_readlane_b32 s79, v255, 11
	v_readlane_b32 s82, v255, 14
	v_readlane_b32 s83, v255, 15
	v_readlane_b32 s84, v255, 16
	v_readlane_b32 s85, v255, 17
	v_readlane_b32 s86, v255, 18
	v_readlane_b32 s87, v255, 19
	v_mad_u64_u32 v[190:191], s[40:41], v74, s46, v[160:161]
	v_mad_i32_i24 v191, v75, s46, v191
	v_lshl_add_u64 v[190:191], v[190:191], 0, s[8:9]
	v_or_b32_e32 v242, s22, v144
	v_mad_i64_i32 v[242:243], s[40:41], v242, s46, v[160:161]
	v_lshl_add_u64 v[242:243], v[242:243], 0, s[8:9]
	v_lshl_add_u64 v[190:191], v[190:191], 0, v[168:169]
	v_lshl_add_u64 v[242:243], v[242:243], 0, s[20:21]
	global_load_dwordx4 v[244:247], v[190:191], off offset:2048
	global_load_dwordx4 v[248:251], v[242:243], off offset:2560
	s_waitcnt vmcnt(0)
	v_lshlrev_b32_e32 v86, 16, v40
	v_and_b32_e32 v87, 0xffff0000, v40
	v_lshlrev_b32_e32 v100, 16, v32
	v_and_b32_e32 v101, 0xffff0000, v32
	v_lshlrev_b32_e32 v96, 16, v33
	v_and_b32_e32 v97, 0xffff0000, v33
	v_pk_mul_f32 v[120:121], v[100:101], v[100:101]
	v_pk_mul_f32 v[116:117], v[96:97], v[96:97]
	v_add_f32_e32 v120, v120, v121
	v_lshlrev_b32_e32 v92, 16, v34
	v_and_b32_e32 v93, 0xffff0000, v34
	v_add_f32_e32 v116, v116, v120
	v_pk_mul_f32 v[112:113], v[92:93], v[92:93]
	v_add_f32_e32 v116, v117, v116
	v_lshlrev_b32_e32 v88, 16, v35
	v_and_b32_e32 v89, 0xffff0000, v35
	v_add_f32_e32 v112, v112, v116
	v_pk_mul_f32 v[108:109], v[88:89], v[88:89]
	v_add_f32_e32 v112, v113, v112
	v_add_f32_e32 v108, v108, v112
	v_pk_mul_f32 v[104:105], v[86:87], v[86:87]
	v_add_f32_e32 v108, v109, v108
	v_lshlrev_b32_e32 v78, 16, v47
	v_and_b32_e32 v79, 0xffff0000, v47
	v_lshlrev_b32_e32 v82, 16, v46
	v_and_b32_e32 v83, 0xffff0000, v46
	v_lshlrev_b32_e32 v46, 16, v41
	v_and_b32_e32 v47, 0xffff0000, v41
	v_add_f32_e32 v104, v104, v108
	v_lshlrev_b32_e32 v76, 16, v43
	v_and_b32_e32 v77, 0xffff0000, v43
	v_lshlrev_b32_e32 v80, 16, v42
	v_and_b32_e32 v81, 0xffff0000, v42
	v_pk_mul_f32 v[42:43], v[46:47], v[46:47]
	v_add_f32_e32 v104, v105, v104
	v_add_f32_e32 v42, v42, v104
	v_pk_mul_f32 v[32:33], v[80:81], v[80:81]
	v_add_f32_e32 v42, v43, v42
	v_add_f32_e32 v32, v32, v42
	v_lshlrev_b32_e32 v98, 16, v29
	v_and_b32_e32 v99, 0xffff0000, v29
	v_lshlrev_b32_e32 v102, 16, v28
	v_and_b32_e32 v103, 0xffff0000, v28
	v_pk_mul_f32 v[28:29], v[76:77], v[76:77]
	v_add_f32_e32 v32, v33, v32
	v_add_f32_e32 v28, v28, v32
	v_pk_mul_f32 v[122:123], v[102:103], v[102:103]
	v_add_f32_e32 v28, v29, v28
	v_add_f32_e32 v28, v122, v28
	v_pk_mul_f32 v[118:119], v[98:99], v[98:99]
	v_add_f32_e32 v28, v123, v28
	v_lshlrev_b32_e32 v94, 16, v30
	v_and_b32_e32 v95, 0xffff0000, v30
	v_add_f32_e32 v28, v118, v28
	v_pk_mul_f32 v[114:115], v[94:95], v[94:95]
	v_add_f32_e32 v28, v119, v28
	v_lshlrev_b32_e32 v90, 16, v31
	v_and_b32_e32 v91, 0xffff0000, v31
	v_add_f32_e32 v28, v114, v28
	v_pk_mul_f32 v[110:111], v[90:91], v[90:91]
	v_add_f32_e32 v28, v115, v28
	v_lshlrev_b32_e32 v40, 16, v44
	v_and_b32_e32 v41, 0xffff0000, v44
	v_add_f32_e32 v28, v110, v28
	v_pk_mul_f32 v[106:107], v[40:41], v[40:41]
	v_add_f32_e32 v28, v111, v28
	v_lshlrev_b32_e32 v84, 16, v45
	v_and_b32_e32 v85, 0xffff0000, v45
	v_add_f32_e32 v28, v106, v28
	v_pk_mul_f32 v[44:45], v[84:85], v[84:85]
	v_add_f32_e32 v28, v107, v28
	v_add_f32_e32 v28, v44, v28
	v_pk_mul_f32 v[34:35], v[82:83], v[82:83]
	v_add_f32_e32 v28, v45, v28
	v_add_f32_e32 v28, v34, v28
	v_pk_mul_f32 v[30:31], v[78:79], v[78:79]
	v_add_f32_e32 v28, v35, v28
	v_add_f32_e32 v28, v30, v28
	v_add_f32_e32 v30, v31, v28
	ds_bpermute_b32 v31, v176, v30
	s_waitcnt lgkmcnt(0)
; __device__ __forceinline__ unsigned pk2(float lo, float hi) { f32x2 v = {lo, hi}; bf16x2_t b = __builtin_convertvector(v, bf16x2_t); return __builtin_bit_cast(unsigned, b); }
; #define LOAD_TILE(ti, kreg, vreg) do { const int k0_ = TILE_K0(ti); const size_t grow_ = ((ti) < 4) ? (size_t)(M_ + b * LCTX + k0_) : (size_t)(b * SEQ + k0_); \
;         kreg = *(const u32x4*)(QKV + (grow_ + krow) * NQKV + 1024 + kvh * 64 + 8 * kch); vreg = *(const u32x4*)(QKV + (grow_ + lane) * NQKV + 1280 + kvh * 64 + 8 * w); } while (0)
; #define LOAD_TILE(ti, kreg, vreg) do { const int k0_ = TILE_K0(ti); const size_t grow_ = ((ti) < 4) ? (size_t)(M_ + b * LCTX + k0_) : (size_t)(b * SEQ + k0_); \
;         kreg = *(const u32x4*)(QKV + (grow_ + krow) * NQKV + 1024 + kvh * 64 + 8 * kch); vreg = *(const u32x4*)(QKV + (grow_ + lane) * NQKV + 1280 + kvh * 64 + 8 * w); } while (0)
;     ...
;             const float rstd = rsqrtf(ss * (1.0f / 64.0f) + 1e-6f);
; #pragma unroll
;             for (int d0 = 0; d0 < 4; ++d0)
; #pragma unroll
;                 for (int i = 0; i < 8; ++i) qf[d0][i] *= rstd * qgain[8 * (2 * d0 + hi) + i];
;             const float* rp = ROPE + (size_t)qrow * 64;
;             float qo[4][8];
; #pragma unroll
;             for (int d0 = 0; d0 < 2; ++d0)
; #pragma unroll
;                 for (int i = 0; i < 8; ++i) { const int j = 8 * (2 * d0 + hi) + i; const float cs = rp[j], sn = rp[32 + j];
;                     qo[d0][i] = qf[d0][i] * cs - qf[d0 + 2][i] * sn; qo[d0 + 2][i] = qf[d0][i] * sn + qf[d0 + 2][i] * cs; }
; #pragma unroll
;             for (int d0 = 0; d0 < 4; ++d0) { u32x4 pw; pw.x = pk2(qo[d0][0] * C2, qo[d0][1] * C2); pw.y = pk2(qo[d0][2] * C2, qo[d0][3] * C2); pw.z = pk2(qo[d0][4] * C2, qo[d0][5] * C2); pw.w = pk2(qo[d0][6] * C2, qo[d0][7] * C2);
;                 qr[d0] = __builtin_bit_cast(bf16x8, pw); }
;         }
;         float m_ref = sink[head] * 1.4426950408889634f; float l_run = hi ? 0.f : 1.f;
;         f32x16 o0 = {}, o1 = {}; f32x16 negm;
; #pragma unroll
;         for (int r = 0; r < 16; ++r) negm[r] = -m_ref;
;         u32x4 kreg, vreg, kreg2, vreg2, kreg3, vreg3;
;     ...
;         LOAD_TILE(0, kreg, vreg); STORE_TILE(0, 0); LOAD_TILE(1, kreg, vreg); LOAD_TILE(2, kreg2, vreg2); LOAD_TILE(3, kreg3, vreg3); __syncthreads();
	v_add_f32_e32 v30, v30, v31
	v_fmamk_f32 v42, v30, 0x3c800000, v180
	v_mul_f32_e32 v43, 0x4b800000, v42
	v_cmp_gt_f32_e32 vcc, s47, v42
	s_add_i32 s22, s39, 0x10040
	s_ashr_i32 s23, s22, 31
	v_cndmask_b32_e32 v42, v42, v43, vcc
	v_rsq_f32_e32 v104, v42
	global_load_dwordx4 v[42:45], v[72:73], off offset:80
	s_nop 0
	global_load_dwordx4 v[72:75], v[72:73], off offset:208
	v_mul_f32_e32 v146, 0x3fb8aa3b, v124
	ds_write_b128 v177, v[244:247]
	v_and_b32_e32 v200, 1, v152
	v_mul_u32_u24_e32 v200, 0x21e, v200
	v_add_u32_e32 v201, v200, v178
	s_mov_b64 s[92:93], vcc
	s_mov_b64 vcc, s[88:89]
	v_cndmask_b32_dpp v192, v250, v248, vcc quad_perm:[1,0,3,2] row_mask:0xf bank_mask:0xf
	v_cndmask_b32_dpp v193, v251, v249, vcc quad_perm:[1,0,3,2] row_mask:0xf bank_mask:0xf
	s_mov_b64 vcc, s[90:91]
	v_cndmask_b32_dpp v194, v248, v250, vcc quad_perm:[1,0,3,2] row_mask:0xf bank_mask:0xf
	v_cndmask_b32_dpp v195, v249, v251, vcc quad_perm:[1,0,3,2] row_mask:0xf bank_mask:0xf
	v_and_b32_e32 v196, 0xffff, v192
	v_lshl_or_b32 v196, v194, 16, v196
	v_lshrrev_b32_e32 v197, 16, v192
	v_and_or_b32 v197, v194, s70, v197
	v_and_b32_e32 v198, 0xffff, v193
	v_lshl_or_b32 v198, v195, 16, v198
	v_lshrrev_b32_e32 v199, 16, v193
	v_and_or_b32 v199, v195, s70, v199
	s_mov_b64 vcc, s[92:93]
	ds_write_b32 v201, v196 offset:18432
	ds_write_b32 v201, v197 offset:18568
	ds_write_b32 v201, v198 offset:18704
	ds_write_b32 v201, v199 offset:18840
	v_mul_f32_e32 v105, 0x45800000, v104
	v_cndmask_b32_e32 v104, v104, v105, vcc
	v_pk_mul_f32 v[36:37], v[36:37], v[104:105] op_sel_hi:[1,0]
	v_pk_mul_f32 v[8:9], v[8:9], v[104:105] op_sel_hi:[1,0]
	v_pk_mul_f32 v[36:37], v[36:37], v[100:101]
	v_pk_mul_f32 v[100:101], v[8:9], v[80:81]
	v_pk_mul_f32 v[8:9], v[10:11], v[104:105] op_sel_hi:[1,0]
	v_pk_mul_f32 v[0:1], v[0:1], v[104:105] op_sel_hi:[1,0]
	v_pk_mul_f32 v[76:77], v[8:9], v[76:77]
	v_pk_mul_f32 v[8:9], v[20:21], v[104:105] op_sel_hi:[1,0]
	v_pk_mul_f32 v[38:39], v[38:39], v[104:105] op_sel_hi:[1,0]
	v_pk_mul_f32 v[12:13], v[12:13], v[104:105] op_sel_hi:[1,0]
	v_pk_mul_f32 v[8:9], v[8:9], v[102:103]
	v_pk_mul_f32 v[10:11], v[22:23], v[104:105] op_sel_hi:[1,0]
	v_pk_mul_f32 v[112:113], v[0:1], v[82:83]
	v_pk_mul_f32 v[0:1], v[2:3], v[104:105] op_sel_hi:[1,0]
	v_pk_mul_f32 v[38:39], v[38:39], v[96:97]
	v_pk_mul_f32 v[24:25], v[24:25], v[104:105] op_sel_hi:[1,0]
	v_pk_mul_f32 v[96:97], v[12:13], v[86:87]
	v_pk_mul_f32 v[12:13], v[14:15], v[104:105] op_sel_hi:[1,0]
	v_pk_mul_f32 v[10:11], v[10:11], v[98:99]
	v_pk_mul_f32 v[78:79], v[0:1], v[78:79]
	v_pk_mul_f32 v[0:1], v[60:61], v[8:9]
	v_pk_mul_f32 v[24:25], v[24:25], v[92:93]
	v_pk_mul_f32 v[26:27], v[26:27], v[104:105] op_sel_hi:[1,0]
	v_pk_mul_f32 v[46:47], v[12:13], v[46:47]
	v_pk_mul_f32 v[12:13], v[16:17], v[104:105] op_sel_hi:[1,0]
	v_pk_fma_f32 v[114:115], v[68:69], v[36:37], v[0:1]
	v_pk_mul_f32 v[0:1], v[62:63], v[10:11]
	v_pk_mul_f32 v[26:27], v[26:27], v[88:89]
	v_pk_mul_f32 v[12:13], v[12:13], v[94:95]
	v_pk_mul_f32 v[14:15], v[18:19], v[104:105] op_sel_hi:[1,0]
	v_pk_fma_f32 v[116:117], v[70:71], v[38:39], v[0:1]
	v_pk_mul_f32 v[0:1], v[64:65], v[24:25]
	v_pk_mul_f32 v[14:15], v[14:15], v[90:91]
	v_pk_fma_f32 v[118:119], v[56:57], v[12:13], v[0:1]
	v_pk_mul_f32 v[0:1], v[26:27], v[66:67]
	v_pk_mul_f32 v[4:5], v[4:5], v[104:105] op_sel_hi:[1,0]
	v_pk_fma_f32 v[120:121], v[14:15], v[58:59], v[0:1]
	v_pk_mul_f32 v[0:1], v[68:69], v[8:9]
	v_pk_mul_f32 v[98:99], v[4:5], v[40:41]
	v_pk_fma_f32 v[0:1], v[60:61], v[36:37], v[0:1] neg_lo:[0,0,1] neg_hi:[0,0,1]
	v_pk_mul_f32 v[4:5], v[6:7], v[104:105] op_sel_hi:[1,0]
	v_pk_mul_f32 v[0:1], v[0:1], s[10:11] op_sel_hi:[1,0]
	v_pk_mul_f32 v[102:103], v[4:5], v[84:85]
	v_cvt_pk_bf16_f32 v80, v0, v1
	v_pk_mul_f32 v[0:1], v[70:71], v[10:11]
	v_lshl_add_u64 v[10:11], s[22:23], 0, v[154:155]
	v_pk_fma_f32 v[0:1], v[62:63], v[38:39], v[0:1] neg_lo:[0,0,1] neg_hi:[0,0,1]
	v_pk_mul_f32 v[16:17], v[102:103], v[54:55]
	v_pk_mul_f32 v[0:1], v[0:1], s[10:11] op_sel_hi:[1,0]
	v_pk_fma_f32 v[16:17], v[46:47], v[50:51], v[16:17] neg_lo:[0,0,1] neg_hi:[0,0,1]
	v_cvt_pk_bf16_f32 v81, v0, v1
	v_pk_mul_f32 v[0:1], v[12:13], v[64:65]
	v_mad_u64_u32 v[12:13], s[40:41], v10, s46, v[160:161]
	v_mad_i32_i24 v13, v11, s46, v13
	v_lshl_add_u64 v[10:11], v[12:13], 0, s[8:9]
	v_or_b32_e32 v12, s22, v144
	v_mad_i64_i32 v[12:13], s[22:23], v12, s46, v[160:161]
	s_add_i32 s22, s39, 0x10080
	v_lshl_add_u64 v[10:11], v[10:11], 0, v[168:169]
	v_lshl_add_u64 v[12:13], v[12:13], 0, s[8:9]
	s_ashr_i32 s23, s22, 31
	v_lshl_add_u64 v[12:13], v[12:13], 0, s[20:21]
	global_load_dwordx4 v[38:41], v[10:11], off offset:2048
	global_load_dwordx4 v[34:37], v[12:13], off offset:2560
	v_lshl_add_u64 v[10:11], s[22:23], 0, v[154:155]
	v_mad_u64_u32 v[12:13], s[40:41], v10, s46, v[160:161]
	v_mad_i32_i24 v13, v11, s46, v13
	v_lshl_add_u64 v[10:11], v[12:13], 0, s[8:9]
	v_or_b32_e32 v12, s22, v144
	v_mad_i64_i32 v[12:13], s[22:23], v12, s46, v[160:161]
	s_add_i32 s22, s39, 0x100c0
	v_lshl_add_u64 v[10:11], v[10:11], 0, v[168:169]
	v_lshl_add_u64 v[12:13], v[12:13], 0, s[8:9]
	s_ashr_i32 s23, s22, 31
	v_lshl_add_u64 v[12:13], v[12:13], 0, s[20:21]
	global_load_dwordx4 v[108:111], v[10:11], off offset:2048
	global_load_dwordx4 v[104:107], v[12:13], off offset:2560
	v_lshl_add_u64 v[10:11], s[22:23], 0, v[154:155]
	v_mad_u64_u32 v[12:13], s[40:41], v10, s46, v[160:161]
	v_mad_i32_i24 v13, v11, s46, v13
	v_lshl_add_u64 v[10:11], v[12:13], 0, s[8:9]
	v_or_b32_e32 v12, s22, v144
	v_mad_i64_i32 v[12:13], s[22:23], v12, s46, v[160:161]
	v_lshl_add_u64 v[10:11], v[10:11], 0, v[168:169]
	v_lshl_add_u64 v[12:13], v[12:13], 0, s[8:9]
	v_pk_fma_f32 v[0:1], v[24:25], v[56:57], v[0:1] neg_lo:[0,0,1] neg_hi:[0,0,1]
	v_lshl_add_u64 v[12:13], v[12:13], 0, s[20:21]
	global_load_dwordx4 v[88:91], v[10:11], off offset:2048
	global_load_dwordx4 v[92:95], v[12:13], off offset:2560
	v_pk_mul_f32 v[0:1], v[0:1], s[10:11] op_sel_hi:[1,0]
	s_waitcnt lgkmcnt(0)
	v_cvt_pk_bf16_f32 v82, v0, v1
	v_pk_mul_f32 v[0:1], v[14:15], v[66:67]
	s_barrier
	v_pk_fma_f32 v[0:1], v[26:27], v[58:59], v[0:1] neg_lo:[0,0,1] neg_hi:[0,0,1]
	ds_read_b128 v[56:59], v145
	v_pk_mul_f32 v[0:1], v[0:1], s[10:11] op_sel_hi:[1,0]
	ds_read_b128 v[60:63], v145 offset:4608
	ds_read_b128 v[64:67], v145 offset:32
	v_cvt_pk_bf16_f32 v83, v0, v1
	v_pk_mul_f32 v[0:1], v[98:99], v[52:53]
	v_pk_mul_f32 v[16:17], v[16:17], s[10:11] op_sel_hi:[1,0]
	v_pk_fma_f32 v[0:1], v[96:97], v[48:49], v[0:1] neg_lo:[0,0,1] neg_hi:[0,0,1]
	v_cvt_pk_bf16_f32 v85, v16, v17
	v_pk_mul_f32 v[0:1], v[0:1], s[10:11] op_sel_hi:[1,0]
	s_waitcnt vmcnt(6)
	v_pk_mul_f32 v[68:69], v[112:113], v[72:73]
	v_cvt_pk_bf16_f32 v84, v0, v1
	v_xor_b32_e32 v0, 0x80000000, v146
	v_mov_b32_e32 v1, v0
	v_mov_b32_e32 v2, v0
	v_mov_b32_e32 v3, v0
	v_mov_b32_e32 v4, v0
	v_mov_b32_e32 v5, v0
	v_mov_b32_e32 v6, v0
	v_mov_b32_e32 v7, v0
	v_mov_b32_e32 v8, v0
	v_mov_b32_e32 v9, v0
	v_mov_b32_e32 v10, v0
	v_mov_b32_e32 v11, v0
	v_mov_b32_e32 v12, v0
	v_mov_b32_e32 v13, v0
	v_mov_b32_e32 v14, v0
	v_mov_b32_e32 v15, v0
	v_pk_mul_f32 v[52:53], v[96:97], v[52:53]
	s_waitcnt lgkmcnt(2)
	v_mfma_f32_32x32x16_bf16 v[18:33], v[56:59], v[80:83], v[0:15]
	v_mov_b64_e32 v[16:17], v[14:15]
	ds_read_b128 v[56:59], v145 offset:4640
	s_nop 4
	v_mov_b64_e32 v[14:15], v[12:13]
	v_mov_b64_e32 v[12:13], v[10:11]
	v_mov_b64_e32 v[10:11], v[8:9]
	v_mov_b64_e32 v[8:9], v[6:7]
	v_mov_b64_e32 v[6:7], v[4:5]
	v_mov_b64_e32 v[4:5], v[2:3]
	v_mov_b64_e32 v[2:3], v[0:1]
	s_waitcnt lgkmcnt(2)
	s_nop 0
	v_mfma_f32_32x32x16_bf16 v[2:17], v[60:63], v[80:83], v[2:17]
	v_fma_f32 v60, v100, v42, -v68
	v_fma_f32 v61, v101, v43, -v69
	v_mul_f32_e64 v62, v46, v54
	v_mul_f32_e64 v63, v47, v55
	v_mul_f32_e64 v60, v60, s10
	v_mul_f32_e64 v61, v61, s10
	v_pk_mul_f32 v[46:47], v[114:115], s[10:11] op_sel_hi:[1,0]
	v_cvt_pk_bf16_f32 v86, v60, v61
	v_pk_mul_f32 v[60:61], v[78:79], v[74:75]
	v_cvt_pk_bf16_f32 v96, v46, v47
	v_pk_fma_f32 v[60:61], v[76:77], v[44:45], v[60:61] neg_lo:[0,0,1] neg_hi:[0,0,1]
	s_nop 0
	v_pk_mul_f32 v[60:61], v[60:61], s[10:11] op_sel_hi:[1,0]
	s_nop 0
	v_cvt_pk_bf16_f32 v87, v60, v61
	v_pk_fma_f32 v[60:61], v[98:99], v[48:49], v[52:53]
	ds_read_b128 v[46:49], v145 offset:64
	s_waitcnt lgkmcnt(2)
	v_mfma_f32_32x32x16_bf16 v[18:33], v[64:67], v[84:87], v[18:33]
	v_mul_f32_e64 v52, v116, s10
	v_mul_f32_e64 v53, v117, s10
	v_mul_f32_e64 v60, v60, s10
	v_mul_f32_e64 v61, v61, s10
	v_cvt_pk_bf16_f32 v97, v52, v53
	v_pk_mul_f32 v[52:53], v[118:119], s[10:11] op_sel_hi:[1,0]
	s_nop 0
	v_cvt_pk_bf16_f32 v98, v52, v53
	v_pk_mul_f32 v[52:53], v[120:121], s[10:11] op_sel_hi:[1,0]
	s_waitcnt lgkmcnt(1)
	v_mfma_f32_32x32x16_bf16 v[2:17], v[56:59], v[84:87], v[2:17]
	v_cvt_pk_bf16_f32 v99, v52, v53
	ds_read_b128 v[52:55], v145 offset:4672
	ds_read_b128 v[56:59], v145 offset:96
	s_waitcnt lgkmcnt(2)
	v_mfma_f32_32x32x16_bf16 v[18:33], v[46:49], v[96:99], v[18:33]
	v_mul_f32_e64 v48, v100, v72
	v_mul_f32_e64 v49, v101, v73
	v_fma_f32 v46, v102, v50, v62
	v_fma_f32 v47, v103, v51, v63
	v_fma_f32 v48, v112, v42, v48
	v_fma_f32 v49, v113, v43, v49
	v_pk_mul_f32 v[42:43], v[76:77], v[74:75]
	v_pk_mul_f32 v[46:47], v[46:47], s[10:11] op_sel_hi:[1,0]
	v_pk_fma_f32 v[50:51], v[78:79], v[44:45], v[42:43]
	ds_read_b128 v[42:45], v145 offset:4704
	s_waitcnt lgkmcnt(2)
	v_mfma_f32_32x32x16_bf16 v[2:17], v[52:55], v[96:99], v[2:17]
	v_cvt_pk_bf16_f32 v101, v46, v47
	v_mul_f32_e64 v46, v48, s10
	v_mul_f32_e64 v47, v49, s10
	v_cvt_pk_bf16_f32 v100, v60, v61
	v_cvt_pk_bf16_f32 v102, v46, v47
	v_pk_mul_f32 v[46:47], v[50:51], s[10:11] op_sel_hi:[1,0]
	s_nop 0
	v_cvt_pk_bf16_f32 v103, v46, v47
	s_waitcnt lgkmcnt(1)
	s_nop 0
	v_mfma_f32_32x32x16_bf16 v[18:33], v[56:59], v[100:103], v[18:33]
	s_waitcnt lgkmcnt(0)
	v_mfma_f32_32x32x16_bf16 v[2:17], v[42:45], v[100:103], v[2:17]
	s_nop 9
	v_max3_f32 v42, v18, v19, v20
	v_max3_f32 v42, v42, v21, v22
	v_max3_f32 v42, v42, v23, v24
	v_max3_f32 v1, v2, v3, v4
	v_max3_f32 v42, v42, v25, v26
	v_max3_f32 v1, v1, v5, v6
	v_max3_f32 v42, v42, v27, v28
	v_max3_f32 v1, v1, v7, v8
	v_max3_f32 v42, v42, v29, v30
	v_max3_f32 v1, v1, v9, v10
	v_max3_f32 v42, v42, v31, v32
	v_max3_f32 v1, v1, v11, v12
	v_max3_f32 v1, v1, v13, v14
	v_max3_f32 v1, v1, v15, v16
	v_max3_f32 v1, v1, v17, v33
	v_max_f32_e32 v1, v1, v42
	ds_bpermute_b32 v42, v176, v1
	s_waitcnt lgkmcnt(0)
	v_max_f32_e32 v42, v42, v42
	v_max_f32_e32 v1, v1, v42
	v_cmp_lt_f32_e32 vcc, s52, v1
	s_cmp_eq_u64 vcc, 0
	s_cselect_b64 s[22:23], -1, 0
	s_cbranch_vccz .LBB0_505
	v_max_f32_e32 v0, v1, v1
	v_max_f32_e32 v42, 0, v0
	v_exp_f32_e64 v44, -v42
	v_add_f32_e32 v146, v146, v42
	v_xor_b32_e32 v0, 0x80000000, v146
	v_pk_add_f32 v[18:19], v[18:19], v[42:43] op_sel_hi:[1,0] neg_lo:[0,1] neg_hi:[0,1]
	v_pk_add_f32 v[2:3], v[2:3], v[42:43] op_sel_hi:[1,0] neg_lo:[0,1] neg_hi:[0,1]
	v_pk_add_f32 v[20:21], v[20:21], v[42:43] op_sel_hi:[1,0] neg_lo:[0,1] neg_hi:[0,1]
	v_pk_add_f32 v[4:5], v[4:5], v[42:43] op_sel_hi:[1,0] neg_lo:[0,1] neg_hi:[0,1]
	v_pk_add_f32 v[22:23], v[22:23], v[42:43] op_sel_hi:[1,0] neg_lo:[0,1] neg_hi:[0,1]
	v_pk_add_f32 v[6:7], v[6:7], v[42:43] op_sel_hi:[1,0] neg_lo:[0,1] neg_hi:[0,1]
	v_pk_add_f32 v[24:25], v[24:25], v[42:43] op_sel_hi:[1,0] neg_lo:[0,1] neg_hi:[0,1]
	v_pk_add_f32 v[8:9], v[8:9], v[42:43] op_sel_hi:[1,0] neg_lo:[0,1] neg_hi:[0,1]
	v_pk_add_f32 v[26:27], v[26:27], v[42:43] op_sel_hi:[1,0] neg_lo:[0,1] neg_hi:[0,1]
	v_pk_add_f32 v[10:11], v[10:11], v[42:43] op_sel_hi:[1,0] neg_lo:[0,1] neg_hi:[0,1]
	v_pk_add_f32 v[28:29], v[28:29], v[42:43] op_sel_hi:[1,0] neg_lo:[0,1] neg_hi:[0,1]
	v_pk_add_f32 v[12:13], v[12:13], v[42:43] op_sel_hi:[1,0] neg_lo:[0,1] neg_hi:[0,1]
	v_pk_add_f32 v[30:31], v[30:31], v[42:43] op_sel_hi:[1,0] neg_lo:[0,1] neg_hi:[0,1]
	v_pk_add_f32 v[14:15], v[14:15], v[42:43] op_sel_hi:[1,0] neg_lo:[0,1] neg_hi:[0,1]
	v_pk_add_f32 v[32:33], v[32:33], v[42:43] op_sel_hi:[1,0] neg_lo:[0,1] neg_hi:[0,1]
	v_pk_add_f32 v[16:17], v[16:17], v[42:43] op_sel_hi:[1,0] neg_lo:[0,1] neg_hi:[0,1]
	v_pk_mul_f32 v[42:43], v[150:151], v[44:45] op_sel_hi:[1,0]
	s_branch .LBB0_506
